# dt_units: column-info loads issued with the row-statistics loads (one round trip instead of two after the reduction barrier)
# baseline (speedup 1.0000x reference)
; #define LAS __attribute__((address_space(3)))
; #define LBAR() do { asm volatile("s_waitcnt lgkmcnt(0)" ::: "memory"); __builtin_amdgcn_s_barrier(); asm volatile("" ::: "memory"); } while (0)
; #define MFMA16(a, b, c) __builtin_amdgcn_mfma_f32_16x16x32_bf16((a), (b), (c), 0, 0, 0)
; __device__ __forceinline__ void dt_units(LAS unsigned char* lds, const bf16_t* xb, const bf16_t* WinT, const float* stat, const float* c1, const float* c2, float* dtbuf, int fold, bf16_t* proj, const int ufirst, const int ustride, const int uend) {
;     ...
;         const bf16_t* ap = xb + (size_t)(u * 64 + rb4 * 16 + fr) * 1024 + kh * 512 + fq * 8;
;         const bf16_t* bp = WinT + (size_t)(NPROJ + fr) * 1024 + kh * 512 + fq * 8;
;         f32x4 acc = (f32x4){0.f, 0.f, 0.f, 0.f};
;         { bf16x8 af[16], bf[16];
; #pragma unroll
;             for (int s = 0; s < 16; ++s) { af[s] = *(const bf16x8*)(ap + s * 32); bf[s] = *(const bf16x8*)(bp + s * 32); }
; #pragma unroll
;             for (int s = 0; s < 16; ++s) acc = MFMA16(bf[s], af[s], acc);
;         }
;         *(LAS f32x4*)(red + (kh * 64 + rb4 * 16 + fr) * 20 + fq * 4) = acc;
;         LBAR();
;         if (tid < 128) {
;             const int r = tid >> 1, c4 = (tid & 1) * 4; const int row = u * 64 + r;
;             f32x4 v = *(const LAS f32x4*)(red + r * 20 + c4) + *(const LAS f32x4*)(red + (64 + r) * 20 + c4);
;             if (fold) {
;                 const f32x4* sp = (const f32x4*)(stat + (size_t)row * 32); float s1 = 0.f, s2 = 0.f;
; #pragma unroll
;                 for (int q = 0; q < 8; ++q) { const f32x4 t = sp[q]; s1 += t[0] + t[2]; s2 += t[1] + t[3]; }
;                 const float mu = s1 * (1.0f / 1024.0f), var = fmaxf(s2 * (1.0f / 1024.0f) - mu * mu, 0.f), rstd = __builtin_amdgcn_rsqf(var + LN_EPS);
;                 const f32x4 k1 = *(const f32x4*)(c1 + NPROJ + c4), k2 = *(const f32x4*)(c2 + NPROJ + c4); v = (v - k1 * mu) * rstd + k2;
.LBB0_921:
	s_or_b64 exec, exec, s[20:21]
	s_lshl_b32 s14, s18, 6
	v_or_b32_e32 v18, s14, v23
	v_ashrrev_i32_e32 v19, 31, v18
	v_lshlrev_b64 v[18:19], 11, v[18:19]
	v_lshl_add_u64 v[64:65], v[2:3], 0, v[18:19]
	global_load_dwordx4 v[18:21], v[12:13], off
	global_load_dwordx4 v[28:31], v[64:65], off
	global_load_dwordx4 v[32:35], v[12:13], off offset:64
	global_load_dwordx4 v[36:39], v[64:65], off offset:64
	global_load_dwordx4 v[40:43], v[12:13], off offset:128
	global_load_dwordx4 v[44:47], v[64:65], off offset:128
	global_load_dwordx4 v[48:51], v[12:13], off offset:192
	global_load_dwordx4 v[52:55], v[64:65], off offset:192
	global_load_dwordx4 v[56:59], v[12:13], off offset:256
	global_load_dwordx4 v[60:63], v[64:65], off offset:256
	global_load_dwordx4 v[88:91], v[12:13], off offset:320
	global_load_dwordx4 v[102:105], v[64:65], off offset:320
	global_load_dwordx4 v[120:123], v[12:13], off offset:384
	global_load_dwordx4 v[138:141], v[64:65], off offset:384
	global_load_dwordx4 v[148:151], v[12:13], off offset:448
	global_load_dwordx4 v[152:155], v[64:65], off offset:448
	global_load_dwordx4 v[160:163], v[12:13], off offset:512
	global_load_dwordx4 v[164:167], v[64:65], off offset:512
	global_load_dwordx4 v[184:187], v[12:13], off offset:576
	global_load_dwordx4 v[188:191], v[64:65], off offset:576
	global_load_dwordx4 v[222:225], v[12:13], off offset:640
	global_load_dwordx4 v[226:229], v[64:65], off offset:640
	global_load_dwordx4 v[230:233], v[12:13], off offset:704
	global_load_dwordx4 v[234:237], v[64:65], off offset:704
	global_load_dwordx4 v[238:241], v[12:13], off offset:768
	global_load_dwordx4 v[242:245], v[64:65], off offset:768
	s_waitcnt vmcnt(24)
	v_mfma_f32_16x16x32_bf16 v[8:11], v[18:21], v[28:31], 0
	global_load_dwordx4 v[18:21], v[12:13], off offset:832
	global_load_dwordx4 v[28:31], v[64:65], off offset:832
	s_waitcnt vmcnt(24)
	v_mfma_f32_16x16x32_bf16 v[8:11], v[32:35], v[36:39], v[8:11]
	global_load_dwordx4 v[32:35], v[12:13], off offset:896
	global_load_dwordx4 v[36:39], v[64:65], off offset:896
	s_waitcnt vmcnt(24)
	v_mfma_f32_16x16x32_bf16 v[8:11], v[40:43], v[44:47], v[8:11]
	global_load_dwordx4 v[40:43], v[12:13], off offset:960
	global_load_dwordx4 v[44:47], v[64:65], off offset:960
	s_waitcnt vmcnt(24)
	v_mfma_f32_16x16x32_bf16 v[8:11], v[48:51], v[52:55], v[8:11]
	s_waitcnt vmcnt(22)
	v_mfma_f32_16x16x32_bf16 v[8:11], v[56:59], v[60:63], v[8:11]
	s_waitcnt vmcnt(20)
	v_mfma_f32_16x16x32_bf16 v[8:11], v[88:91], v[102:105], v[8:11]
	s_waitcnt vmcnt(18)
	v_mfma_f32_16x16x32_bf16 v[8:11], v[120:123], v[138:141], v[8:11]
	s_waitcnt vmcnt(16)
	v_mfma_f32_16x16x32_bf16 v[8:11], v[148:151], v[152:155], v[8:11]
	s_waitcnt vmcnt(14)
	v_mfma_f32_16x16x32_bf16 v[8:11], v[160:163], v[164:167], v[8:11]
	s_waitcnt vmcnt(12)
	v_mfma_f32_16x16x32_bf16 v[8:11], v[184:187], v[188:191], v[8:11]
	s_waitcnt vmcnt(10)
	v_mfma_f32_16x16x32_bf16 v[8:11], v[222:225], v[226:229], v[8:11]
	s_waitcnt vmcnt(8)
	v_mfma_f32_16x16x32_bf16 v[8:11], v[230:233], v[234:237], v[8:11]
	s_waitcnt vmcnt(6)
	v_mfma_f32_16x16x32_bf16 v[8:11], v[238:241], v[242:245], v[8:11]
	s_waitcnt vmcnt(4)
	v_mfma_f32_16x16x32_bf16 v[8:11], v[18:21], v[28:31], v[8:11]
	s_waitcnt vmcnt(2)
	v_mfma_f32_16x16x32_bf16 v[8:11], v[32:35], v[36:39], v[8:11]
	s_waitcnt vmcnt(0)
	v_mfma_f32_16x16x32_bf16 v[8:11], v[40:43], v[44:47], v[8:11]
	s_nop 7
	ds_write_b128 v26, v[8:11]
	s_waitcnt lgkmcnt(0)
	s_barrier
	s_and_saveexec_b64 s[20:21], s[42:43]
	s_cbranch_execz .LBB0_917
	ds_read_b128 v[28:31], v25
	ds_read_b128 v[32:35], v25 offset:5120
	v_add_u32_e32 v18, s14, v24
	s_and_b64 vcc, exec, s[40:41]
	v_ashrrev_i32_e32 v19, 31, v18
	s_waitcnt lgkmcnt(0)
	v_pk_add_f32 v[8:9], v[30:31], v[34:35]
	v_pk_add_f32 v[20:21], v[28:29], v[32:33]
	s_cbranch_vccnz .LBB0_924
	v_lshlrev_b64 v[10:11], 7, v[18:19]
	v_lshl_add_u64 v[10:11], s[34:35], 0, v[10:11]
	global_load_dwordx4 v[28:31], v[10:11], off offset:48
	global_load_dwordx4 v[32:35], v[10:11], off offset:32
	global_load_dwordx4 v[36:39], v[10:11], off offset:16
	global_load_dwordx4 v[40:43], v[10:11], off
	global_load_dwordx4 v[44:47], v[10:11], off offset:112
	global_load_dwordx4 v[48:51], v[10:11], off offset:96
	global_load_dwordx4 v[52:55], v[10:11], off offset:80
	global_load_dwordx4 v[56:59], v[10:11], off offset:64
	global_load_dwordx4 v[88:91], v[14:15], off
	global_load_dwordx4 v[102:105], v[16:17], off
	s_waitcnt vmcnt(9)
	v_pk_add_f32 v[28:29], v[28:29], v[30:31]
	s_waitcnt vmcnt(8)
	v_pk_add_f32 v[32:33], v[32:33], v[34:35]
	s_waitcnt vmcnt(7)
	v_pk_add_f32 v[36:37], v[36:37], v[38:39]
	s_waitcnt vmcnt(6)
	v_pk_add_f32 v[10:11], v[40:41], v[42:43]
	s_nop 0
	v_pk_add_f32 v[10:11], v[10:11], 0 op_sel_hi:[1,0]
	s_nop 0
	v_pk_add_f32 v[10:11], v[10:11], v[36:37]
	s_nop 0
	v_pk_add_f32 v[10:11], v[10:11], v[32:33]
	s_nop 0
	v_pk_add_f32 v[10:11], v[10:11], v[28:29]
	s_waitcnt vmcnt(2)
	v_pk_add_f32 v[28:29], v[56:57], v[58:59]
	s_nop 0
	v_pk_add_f32 v[10:11], v[10:11], v[28:29]
	v_pk_add_f32 v[28:29], v[52:53], v[54:55]
	s_nop 0
	v_pk_add_f32 v[10:11], v[10:11], v[28:29]
	v_pk_add_f32 v[28:29], v[48:49], v[50:51]
	s_nop 0
	v_pk_add_f32 v[10:11], v[10:11], v[28:29]
	v_pk_add_f32 v[28:29], v[44:45], v[46:47]
	s_nop 0
	v_pk_add_f32 v[10:11], v[10:11], v[28:29]
	v_pk_mul_f32 v[10:11], v[10:11], s[0:1] op_sel_hi:[1,0]
	s_nop 0
	v_fma_f32 v0, -v10, v10, v11
	v_max_f32_e32 v0, 0, v0
	v_add_f32_e32 v0, 0x3727c5ac, v0
	v_rsq_f32_e32 v0, v0
	s_waitcnt vmcnt(1)
	v_pk_fma_f32 v[20:21], v[88:89], v[10:11], v[20:21] op_sel_hi:[1,0,1] neg_lo:[1,0,0] neg_hi:[1,0,0]
	v_xor_b32_e32 v29, 0x80000000, v91
	v_xor_b32_e32 v28, 0x80000000, v90
	v_pk_fma_f32 v[8:9], v[28:29], v[10:11], v[8:9] op_sel_hi:[1,0,1]
	s_waitcnt vmcnt(0)
	v_pk_fma_f32 v[20:21], v[20:21], v[0:1], v[102:103] op_sel_hi:[1,0,1]
	v_pk_fma_f32 v[8:9], v[8:9], v[0:1], v[104:105] op_sel_hi:[1,0,1]
